# diff-attention key loop slimmed: bf16 pack via v_cvt_pk_bf16_f32 (same RNE), dropped redundant -1e29 guards (running max always finite since key 0 visible); hazard pads re-derived
# speedup vs baseline: 1.1484x; 1.0376x over previous
; DI uint4 gld16(const void* p) { uint4 r; asm volatile("global_load_dwordx4 %0, %1, off" : "=v"(r) : "v"(p) : "memory"); return r; }
; DI void vm_wait0() { asm volatile("s_waitcnt vmcnt(0)" ::: "memory"); }
; DI int crow(int i, int h) { return (i & 3) + 8 * (i >> 2) + 4 * h; }
; #define MFMA32(a, b, c) __builtin_amdgcn_mfma_f32_32x32x16_bf16((a), (b), (c), 0, 0, 0)
; DI void kv_wait(KVRegs& rg) { asm volatile("s_waitcnt vmcnt(0)" : "+v"(rg.k[0]), "+v"(rg.k[1]), "+v"(rg.v[0]), "+v"(rg.v[1]) :: "memory"); }
; template <int DQK>
; DI void attn_tile_step(const bf16_t* sK, const bf16_t* sV, const bf16x8 (&qf)[DQK / 16], int k0, int qpos, int window, float sl2, float& m, float& lsum, f32x16 (&O)[2], int r, int h) {
;     ...
;     for (int ks = 0; ks < NKS; ++ks) { const bf16x8 a = *(const bf16x8*)(sK + (t2 * 32 + r) * LDK + ks * 16 + 8 * h); s[t2] = MFMA32(a, qf[ks], s[t2]); }
;   }
;   float mx = m;
; #pragma unroll
;   for (int t2 = 0; t2 < 2; ++t2)
; #pragma unroll
;     for (int i = 0; i < 16; ++i) { const int kpos = k0 + t2 * 32 + crow(i, h); const bool ok = (kpos <= qpos) && (window == 0 || qpos - kpos < window);
;       const float v = ok ? s[t2][i] * sl2 : -1e30f; s[t2][i] = v; mx = fmaxf(mx, v); }
; DI void diff_item(const Params& p, int l, int b, int hh, int qb, char* smem) {
;     ...
;   for (int kt = 0; kt < kt1; ++kt) {
;     const int k0 = kt * 64;
;     kv_wait(rg); vm_wait0();
;     __syncthreads();
;     kv_commit<32>(rg, sK1, sV); *(uint4*)(sK2 + (tid >> 2) * 40 + (tid & 3) * 8) = rk2;
;     __syncthreads();
;     { const int kn = (kt + 1 < kt1 ? kt + 1 : kt) * 64; kv_issue<32>(K1g, vt, kn, rg); rk2 = gld16(K2g + (size_t)(kn + (tid >> 2)) * LDP + (tid & 3) * 8); }
;     if (k0 > qw0 + 31) continue;
;     attn_tile_step<32>(sK1, sV, qf1, k0, qpos, 0, sl2, m1, l1, O1, r, h);
.LBB0_537:
	s_waitcnt vmcnt(0)
	v_mov_b32_e32 v66, v170
	s_waitcnt vmcnt(0)
	s_barrier
	s_mov_b32 s2, s37
	v_lshlrev_b32_e32 v67, 4, v66
	v_lshrrev_b32_e32 v65, 2, v66
	v_and_b32_e32 v64, 48, v67
	v_mad_u64_u32 v[64:65], s[0:1], v65, s12, v[64:65]
	v_lshrrev_b32_e32 v65, 3, v66
	ds_write_b128 v64, v[112:115]
	v_and_b32_e32 v64, 0x70, v67
	v_mul_lo_u32 v65, v65, s22
	v_add3_u32 v65, v64, v65, s23
	ds_write2_b64 v65, v[120:121], v[122:123] offset1:1
	v_add_u32_e32 v65, 0x100, v66
	s_add_i32 s37, s37, 1
	v_lshrrev_b32_e32 v65, 3, v65
	s_cmp_ge_u32 s37, s36
	v_mul_lo_u32 v65, v65, s22
	s_cselect_b64 s[8:9], -1, 0
	s_cmp_lt_u32 s37, s36
	v_add3_u32 v64, v64, v65, s23
	s_cselect_b32 s0, s37, s2
	v_mov_b32_e32 v70, v170
	ds_write2_b64 v64, v[124:125], v[126:127] offset1:1
	s_lshl_b32 s2, s0, 6
	ds_write_b128 v208, v[116:119] offset:5120
	s_waitcnt lgkmcnt(0)
	s_barrier
	s_movk_i32 s6, 0x1a00
	v_ashrrev_i32_e32 v66, 2, v70
	v_add_u32_e32 v68, s2, v66
	v_mov_b64_e32 v[66:67], s[34:35]
	v_mad_i64_i32 v[66:67], s[4:5], v68, s6, v[66:67]
	v_lshlrev_b32_e32 v68, 4, v70
	s_lshl_b64 s[0:1], s[2:3], 1
	v_and_b32_e32 v142, 48, v68
	s_add_u32 s0, s30, s0
	v_lshl_add_u64 v[66:67], v[66:67], 0, v[142:143]
	s_addc_u32 s1, s31, s1
	v_lshl_add_u64 v[66:67], v[66:67], 0, s[14:15]
	v_and_b32_e32 v142, 0x70, v68
	global_load_dwordx4 v[112:115], v[66:67], off
	v_lshl_add_u64 v[66:67], s[0:1], 0, v[142:143]
	v_ashrrev_i32_e32 v68, 3, v70
	v_mad_i64_i32 v[68:69], s[0:1], v68, s13, v[66:67]
	global_load_dwordx4 v[120:123], v[68:69], off
	v_add_u32_e32 v68, 0x100, v70
	v_ashrrev_i32_e32 v68, 3, v68
	v_add_u32_e32 v64, s2, v204
	v_mad_i64_i32 v[66:67], s[0:1], v68, s13, v[66:67]
	global_load_dwordx4 v[124:127], v[66:67], off
	v_mad_i64_i32 v[64:65], s[4:5], v64, s6, v[148:149]
	global_load_dwordx4 v[116:119], v[64:65], off
	v_cmp_le_i32_e32 vcc, s21, v205
	s_and_saveexec_b64 s[6:7], vcc
	s_cbranch_execz .LBB0_536
	ds_read_b128 v[64:67], v206
	ds_read_b128 v[80:83], v206 offset:32
	v_cmp_lt_i32_e32 vcc, v180, v179
	v_add_u32_e32 v142, s21, v203
	v_or_b32_e32 v153, 49, v142
	s_waitcnt vmcnt(3) lgkmcnt(1)
	v_mfma_f32_32x32x16_bf16 v[64:79], v[64:67], v[96:99], 0
	v_cndmask_b32_e32 v84, v177, v180, vcc
	v_lshlrev_b32_e32 v152, 2, v84
	v_or_b32_e32 v158, 48, v142
	s_mov_b32 s2, 0x3e8293ee
	v_cmp_gt_i32_e64 s[0:1], v153, v145
	v_cmp_gt_i32_e64 s[38:39], v158, v140
	v_cmp_gt_i32_e64 s[84:85], v140, v142
	s_waitcnt vmcnt(1) lgkmcnt(0)
	v_mfma_f32_32x32x16_bf16 v[64:79], v[80:83], v[104:107], v[64:79]
	ds_read_b128 v[80:83], v206 offset:2560
	ds_read_b128 v[154:157], v206 offset:2592
	v_cmp_gt_i32_e64 s[86:87], v142, v140
	v_add_u32_e32 v209, 0x2800, v207
	ds_read2_b64 v[136:139], v209 offset1:2
	ds_read2_b64 v[132:135], v209 offset0:4 offset1:6
	v_add_u32_e32 v210, 0x3800, v207
	s_nop 4
	v_mul_f32_e32 v159, 0x3e8293ee, v64
	s_waitcnt lgkmcnt(3)
	v_mfma_f32_32x32x16_bf16 v[80:95], v[80:83], v[96:99], 0
	v_mul_f32_e32 v160, 0x3e8293ee, v65
	v_cndmask_b32_e64 v160, v189, v160, s[84:85]
	v_cndmask_b32_e64 v159, v159, v189, s[86:87]
	s_waitcnt lgkmcnt(2)
	v_mfma_f32_32x32x16_bf16 v[80:95], v[154:157], v[104:107], v[80:95]
	s_nop 11
	v_pk_mul_f32 v[64:65], v[88:89], s[2:3] op_sel_hi:[1,0]
	v_or_b32_e32 v88, 51, v142
	v_or_b32_e32 v89, 50, v142
	v_cndmask_b32_e64 v153, v65, v189, s[0:1]
	v_cndmask_b32_e64 v154, v64, v189, s[38:39]
	v_pk_mul_f32 v[64:65], v[90:91], s[2:3] op_sel_hi:[1,0]
	v_cmp_gt_i32_e64 s[40:41], v88, v145
	v_cmp_gt_i32_e64 s[42:43], v89, v140
	v_or_b32_e32 v88, 57, v142
	v_or_b32_e32 v89, 56, v142
	v_cndmask_b32_e64 v156, v65, v189, s[40:41]
	v_cndmask_b32_e64 v158, v64, v189, s[42:43]
	v_pk_mul_f32 v[64:65], v[92:93], s[2:3] op_sel_hi:[1,0]
	v_cmp_gt_i32_e64 s[44:45], v88, v145
	v_cmp_gt_i32_e64 s[46:47], v89, v140
	v_or_b32_e32 v88, 59, v142
	v_or_b32_e32 v89, 58, v142
	v_cndmask_b32_e64 v90, v65, v189, s[44:45]
	v_cndmask_b32_e64 v91, v64, v189, s[46:47]
	v_pk_mul_f32 v[64:65], v[94:95], s[2:3] op_sel_hi:[1,0]
	v_cmp_gt_i32_e64 s[48:49], v88, v145
	v_cmp_gt_i32_e64 s[50:51], v89, v140
	v_or_b32_e32 v92, 33, v142
	v_or_b32_e32 v93, 32, v142
	v_cndmask_b32_e64 v88, v65, v189, s[48:49]
	v_cndmask_b32_e64 v89, v64, v189, s[50:51]
	v_pk_mul_f32 v[64:65], v[80:81], s[2:3] op_sel_hi:[1,0]
	v_cmp_gt_i32_e64 s[52:53], v92, v145
	v_cmp_gt_i32_e64 s[54:55], v93, v140
	v_or_b32_e32 v92, 35, v142
	v_or_b32_e32 v93, 34, v142
	v_cndmask_b32_e64 v80, v65, v189, s[52:53]
	v_cndmask_b32_e64 v81, v64, v189, s[54:55]
	v_pk_mul_f32 v[64:65], v[82:83], s[2:3] op_sel_hi:[1,0]
	v_cmp_gt_i32_e64 s[56:57], v92, v145
	v_cmp_gt_i32_e64 s[58:59], v93, v140
	v_or_b32_e32 v92, 41, v142
	v_or_b32_e32 v93, 40, v142
	v_cndmask_b32_e64 v82, v65, v189, s[56:57]
	v_cndmask_b32_e64 v83, v64, v189, s[58:59]
	v_pk_mul_f32 v[64:65], v[84:85], s[2:3] op_sel_hi:[1,0]
	v_cmp_gt_i32_e64 s[60:61], v92, v145
	v_cmp_gt_i32_e64 s[62:63], v93, v140
	v_or_b32_e32 v92, 43, v142
	v_or_b32_e32 v93, 42, v142
	v_cndmask_b32_e64 v84, v65, v189, s[60:61]
	v_cndmask_b32_e64 v85, v64, v189, s[62:63]
	v_pk_mul_f32 v[64:65], v[86:87], s[2:3] op_sel_hi:[1,0]
	v_cmp_gt_i32_e64 s[64:65], v92, v145
	v_cmp_gt_i32_e64 s[66:67], v93, v140
	v_or_b32_e32 v92, 17, v142
	v_or_b32_e32 v93, 16, v142
	v_cndmask_b32_e64 v86, v65, v189, s[64:65]
	v_cndmask_b32_e64 v87, v64, v189, s[66:67]
	v_pk_mul_f32 v[64:65], v[72:73], s[2:3] op_sel_hi:[1,0]
	v_cmp_gt_i32_e64 s[68:69], v92, v145
	v_cmp_gt_i32_e64 s[70:71], v93, v140
	v_or_b32_e32 v72, 19, v142
	v_or_b32_e32 v73, 18, v142
	v_cndmask_b32_e64 v92, v65, v189, s[68:69]
	v_cndmask_b32_e64 v93, v64, v189, s[70:71]
	v_pk_mul_f32 v[64:65], v[74:75], s[2:3] op_sel_hi:[1,0]
; DI bf16_t f2bf(float f) { unsigned u = __float_as_uint(f); u += 0x7fffu + ((u >> 16) & 1u); return (bf16_t)(u >> 16); }
; DI float fexp2(float x) { return __builtin_amdgcn_exp2f(x); }
; DI int crow(int i, int h) { return (i & 3) + 8 * (i >> 2) + 4 * h; }
; #define MFMA32(a, b, c) __builtin_amdgcn_mfma_f32_32x32x16_bf16((a), (b), (c), 0, 0, 0)
; DI bf16x8 pack8(const f32x16& x, int s) {
;     ...
;   for (int j = 0; j < 8; ++j) r[j] = (short)f2bf(x[8 * s + j]);
;   return r;
; }
; DI void pv_accum(const f32x16 (&s)[2], const bf16_t* sV, int r, int h, f32x16 (&O)[2]) {
; #pragma unroll
;   for (int t2 = 0; t2 < 2; ++t2)
; #pragma unroll
;     for (int s2 = 0; s2 < 2; ++s2) {
;       const bf16x8 pf = pack8(s[t2], s2);
; #pragma unroll
;       for (int dt = 0; dt < 2; ++dt) {
;         const bf16_t* vp = sV + (dt * 32 + r) * 68 + t2 * 32 + 16 * s2 + 4 * h;
;         const s16x4 lo = *(const s16x4*)vp, hi = *(const s16x4*)(vp + 8);
;         const bf16x8 vf = __builtin_shufflevector(lo, hi, 0, 1, 2, 3, 4, 5, 6, 7);
;         O[dt] = MFMA32(vf, pf, O[dt]);
; template <int DQK>
; DI void attn_tile_step(const bf16_t* sK, const bf16_t* sV, const bf16x8 (&qf)[DQK / 16], int k0, int qpos, int window, float sl2, float& m, float& lsum, f32x16 (&O)[2], int r, int h) {
;     ...
;     for (int i = 0; i < 16; ++i) { const int kpos = k0 + t2 * 32 + crow(i, h); const bool ok = (kpos <= qpos) && (window == 0 || qpos - kpos < window);
;       const float v = ok ? s[t2][i] * sl2 : -1e30f; s[t2][i] = v; mx = fmaxf(mx, v); }
;   mx = fmaxf(mx, __shfl_xor(mx, 32));
;   const float corr = fexp2(m - mx); m = mx; float ps = 0.f;
; #pragma unroll
;   for (int t2 = 0; t2 < 2; ++t2)
; #pragma unroll
;     for (int i = 0; i < 16; ++i) { const float pv = (s[t2][i] > -1e29f) ? fexp2(s[t2][i] - mx) : 0.f; s[t2][i] = pv; ps += pv; }
;   lsum = lsum * corr + ps;
; #pragma unroll
;   for (int dt = 0; dt < 2; ++dt)
; #pragma unroll
;     for (int i = 0; i < 16; ++i) O[dt][i] *= corr;
;   pv_accum(s, sV, r, h, O);
	v_cmp_gt_i32_e64 s[72:73], v72, v145
	v_cmp_gt_i32_e64 s[74:75], v73, v140
	v_or_b32_e32 v72, 25, v142
	v_or_b32_e32 v73, 24, v142
	v_cndmask_b32_e64 v94, v65, v189, s[72:73]
	v_cndmask_b32_e64 v95, v64, v189, s[74:75]
	v_pk_mul_f32 v[64:65], v[76:77], s[2:3] op_sel_hi:[1,0]
	v_cmp_gt_i32_e64 s[76:77], v72, v145
	v_cmp_gt_i32_e64 s[78:79], v73, v140
	v_or_b32_e32 v72, 27, v142
	v_or_b32_e32 v73, 26, v142
	v_cndmask_b32_e64 v155, v65, v189, s[76:77]
	v_cndmask_b32_e64 v157, v64, v189, s[78:79]
	v_pk_mul_f32 v[64:65], v[78:79], s[2:3] op_sel_hi:[1,0]
	v_cmp_gt_i32_e64 s[80:81], v72, v145
	v_cmp_gt_i32_e64 s[82:83], v73, v140
	v_or_b32_e32 v73, 3, v142
	v_or_b32_e32 v74, 2, v142
	v_cndmask_b32_e64 v161, v65, v189, s[80:81]
	v_cndmask_b32_e64 v162, v64, v189, s[82:83]
	v_pk_mul_f32 v[64:65], v[66:67], s[2:3] op_sel_hi:[1,0]
	v_cmp_gt_i32_e64 s[88:89], v73, v145
	v_cmp_gt_i32_e64 s[90:91], v74, v140
	v_max3_f32 v72, v151, v159, v160
	v_cndmask_b32_e64 v163, v65, v189, s[88:89]
	v_cndmask_b32_e64 v164, v64, v189, s[90:91]
	v_max3_f32 v66, v72, v164, v163
	v_or_b32_e32 v67, 9, v142
	v_or_b32_e32 v72, 8, v142
	v_pk_mul_f32 v[64:65], v[68:69], s[2:3] op_sel_hi:[1,0]
	v_cmp_gt_i32_e64 s[92:93], v67, v145
	v_cmp_gt_i32_e64 s[94:95], v72, v140
	v_or_b32_e32 v67, 11, v142
	v_or_b32_e32 v68, 10, v142
	v_cndmask_b32_e64 v165, v65, v189, s[92:93]
	v_cndmask_b32_e64 v166, v64, v189, s[94:95]
	v_pk_mul_f32 v[64:65], v[70:71], s[2:3] op_sel_hi:[1,0]
	v_cmp_gt_i32_e64 s[96:97], v67, v145
	v_cmp_gt_i32_e32 vcc, v68, v140
	v_max3_f32 v66, v66, v166, v165
	v_cndmask_b32_e64 v142, v65, v189, s[96:97]
	v_cndmask_b32_e32 v167, v64, v189, vcc
	v_max3_f32 v64, v66, v167, v142
	v_max3_f32 v64, v64, v93, v92
	v_max3_f32 v64, v64, v95, v94
	v_max3_f32 v64, v64, v157, v155
	v_max3_f32 v64, v64, v162, v161
	v_max3_f32 v64, v64, v81, v80
	v_max3_f32 v64, v64, v83, v82
	v_max3_f32 v64, v64, v85, v84
	v_max3_f32 v64, v64, v87, v86
	v_max3_f32 v64, v64, v154, v153
	v_max3_f32 v64, v64, v158, v156
	v_max3_f32 v64, v64, v91, v90
	v_max3_f32 v168, v64, v89, v88
	ds_bpermute_b32 v169, v152, v168
	ds_read2_b64 v[76:79], v210 offset0:32 offset1:34
	ds_read2_b64 v[72:75], v210 offset0:36 offset1:38
	ds_read2_b64 v[68:71], v209 offset0:8 offset1:10
	ds_read2_b64 v[64:67], v210 offset0:40 offset1:42
	s_waitcnt lgkmcnt(4)
	v_max_f32_e32 v169, v169, v169
	v_max_f32_e32 v211, v168, v169
	v_sub_f32_e32 v168, v151, v211
	v_sub_f32_e32 v151, v160, v211
	v_exp_f32_e32 v151, v151
	v_sub_f32_e32 v169, v159, v211
	v_exp_f32_e32 v169, v169
	v_sub_f32_e32 v216, v164, v211
	v_mov_b32_e32 v160, v151
	v_sub_f32_e32 v159, v163, v211
	v_exp_f32_e32 v159, v159
	v_exp_f32_e32 v216, v216
	v_mov_b32_e32 v169, v169
	v_add_f32_e32 v151, 0, v169
	v_add_f32_e32 v151, v160, v151
	v_mov_b32_e32 v163, v159
	v_sub_f32_e32 v159, v165, v211
	v_exp_f32_e32 v159, v159
	v_mov_b32_e32 v164, v216
	v_sub_f32_e32 v216, v166, v211
	v_exp_f32_e32 v216, v216
	v_add_f32_e32 v151, v164, v151
	v_add_f32_e32 v151, v163, v151
	v_mov_b32_e32 v165, v159
	v_sub_f32_e32 v159, v142, v211
	v_exp_f32_e32 v159, v159
	v_mov_b32_e32 v166, v216
	v_sub_f32_e32 v216, v167, v211
	v_exp_f32_e32 v216, v216
	v_add_f32_e32 v151, v166, v151
	v_add_f32_e32 v151, v165, v151
	v_mov_b32_e32 v217, v159
	v_sub_f32_e32 v159, v93, v211
	v_exp_f32_e32 v159, v159
	v_mov_b32_e32 v167, v216
	v_add_f32_e32 v142, v167, v151
	v_sub_f32_e32 v151, v92, v211
	v_exp_f32_e32 v151, v151
	v_add_f32_e32 v142, v217, v142
	s_nop 0
	v_mov_b32_e32 v92, v151
	v_sub_f32_e32 v151, v94, v211
	v_exp_f32_e32 v151, v151
	s_nop 1
	v_mov_b32_e32 v93, v159
	v_sub_f32_e32 v159, v95, v211
	v_exp_f32_e32 v159, v159
	v_add_f32_e32 v142, v93, v142
	v_mov_b32_e32 v94, v151
	v_sub_f32_e32 v151, v155, v211
	v_exp_f32_e32 v151, v151
	v_add_f32_e32 v142, v92, v142
	s_nop 0
	v_mov_b32_e32 v95, v159
	v_sub_f32_e32 v159, v157, v211
	v_exp_f32_e32 v159, v159
	v_sub_f32_e32 v155, v162, v211
	v_mov_b32_e32 v216, v151
	v_sub_f32_e32 v151, v161, v211
	v_exp_f32_e32 v151, v151
	v_exp_f32_e32 v155, v155
	v_add_f32_e32 v142, v95, v142
	v_add_f32_e32 v142, v94, v142
	s_nop 0
	v_mov_b32_e32 v218, v159
	v_add_f32_e32 v142, v218, v142
	v_add_f32_e32 v142, v216, v142
	v_mov_b32_e32 v161, v151
	v_sub_f32_e32 v151, v81, v211
	v_exp_f32_e32 v151, v151
	v_mov_b32_e32 v162, v155
	v_add_f32_e32 v142, v162, v142
	v_add_f32_e32 v219, v161, v142
	v_sub_f32_e32 v142, v80, v211
	v_exp_f32_e32 v142, v142
	v_sub_f32_e32 v80, v82, v211
	v_exp_f32_e32 v80, v80
	v_mov_b32_e32 v220, v142
	v_sub_f32_e32 v81, v83, v211
	v_exp_f32_e32 v81, v81
	v_mov_b32_e32 v221, v151
	v_exp_f32_e32 v142, v168
	v_mov_b32_e32 v222, v80
	v_sub_f32_e32 v80, v84, v211
	v_exp_f32_e32 v80, v80
	v_mov_b32_e32 v223, v81
	v_sub_f32_e32 v81, v85, v211
	v_exp_f32_e32 v81, v81
	v_pk_mul_f32 v[48:49], v[48:49], v[142:143] op_sel_hi:[1,0]
	v_mov_b32_e32 v84, v80
	v_sub_f32_e32 v80, v86, v211
	v_exp_f32_e32 v80, v80
	v_mov_b32_e32 v85, v81
	v_sub_f32_e32 v81, v87, v211
	v_exp_f32_e32 v81, v81
	v_pk_mul_f32 v[50:51], v[50:51], v[142:143] op_sel_hi:[1,0]
	v_pk_mul_f32 v[52:53], v[52:53], v[142:143] op_sel_hi:[1,0]
	v_mov_b32_e32 v159, v80
	v_sub_f32_e32 v80, v153, v211
	v_exp_f32_e32 v80, v80
	v_mov_b32_e32 v86, v81
	v_sub_f32_e32 v81, v154, v211
	v_exp_f32_e32 v81, v81
	v_pk_mul_f32 v[54:55], v[54:55], v[142:143] op_sel_hi:[1,0]
	v_pk_mul_f32 v[56:57], v[56:57], v[142:143] op_sel_hi:[1,0]
	v_mov_b32_e32 v155, v80
	v_sub_f32_e32 v80, v156, v211
	v_exp_f32_e32 v80, v80
	v_mov_b32_e32 v157, v81
	v_sub_f32_e32 v81, v158, v211
	v_exp_f32_e32 v81, v81
	v_mov_b32_e32 v151, v80
	v_sub_f32_e32 v80, v90, v211
	v_exp_f32_e32 v87, v80
	v_mov_b32_e32 v153, v81
	v_pk_mul_f32 v[58:59], v[58:59], v[142:143] op_sel_hi:[1,0]
	v_pk_mul_f32 v[60:61], v[60:61], v[142:143] op_sel_hi:[1,0]
	v_pk_mul_f32 v[62:63], v[62:63], v[142:143] op_sel_hi:[1,0]
	v_cvt_pk_bf16_f32 v83, v167, v217
	v_cvt_pk_bf16_f32 v82, v166, v165
	v_cvt_pk_bf16_f32 v81, v164, v163
	v_cvt_pk_bf16_f32 v80, v169, v160
	v_pk_mul_f32 v[16:17], v[16:17], v[142:143] op_sel_hi:[1,0]
	v_pk_mul_f32 v[18:19], v[18:19], v[142:143] op_sel_hi:[1,0]
	v_mfma_f32_32x32x16_bf16 v[48:63], v[136:139], v[80:83], v[48:63]
	v_mul_f32_e64 v20, v20, v142
	v_mul_f32_e64 v21, v21, v142
	v_mul_f32_e64 v22, v22, v142
	v_mul_f32_e64 v23, v23, v142
	v_mul_f32_e64 v24, v24, v142
	v_mul_f32_e64 v25, v25, v142
	v_pk_mul_f32 v[26:27], v[26:27], v[142:143] op_sel_hi:[1,0]
	v_pk_mul_f32 v[28:29], v[28:29], v[142:143] op_sel_hi:[1,0]
	v_pk_mul_f32 v[30:31], v[30:31], v[142:143] op_sel_hi:[1,0]
	s_waitcnt lgkmcnt(3)
; DI int crow(int i, int h) { return (i & 3) + 8 * (i >> 2) + 4 * h; }
; #define MFMA32(a, b, c) __builtin_amdgcn_mfma_f32_32x32x16_bf16((a), (b), (c), 0, 0, 0)
; DI void pv_accum(const f32x16 (&s)[2], const bf16_t* sV, int r, int h, f32x16 (&O)[2]) {
;     ...
;       const bf16x8 pf = pack8(s[t2], s2);
; #pragma unroll
;       for (int dt = 0; dt < 2; ++dt) {
;         const bf16_t* vp = sV + (dt * 32 + r) * 68 + t2 * 32 + 16 * s2 + 4 * h;
;         const s16x4 lo = *(const s16x4*)vp, hi = *(const s16x4*)(vp + 8);
;         const bf16x8 vf = __builtin_shufflevector(lo, hi, 0, 1, 2, 3, 4, 5, 6, 7);
;         O[dt] = MFMA32(vf, pf, O[dt]);
; template <int DQK>
; DI void attn_tile_step(const bf16_t* sK, const bf16_t* sV, const bf16x8 (&qf)[DQK / 16], int k0, int qpos, int window, float sl2, float& m, float& lsum, f32x16 (&O)[2], int r, int h) {
;     ...
;     for (int ks = 0; ks < NKS; ++ks) { const bf16x8 a = *(const bf16x8*)(sK + (t2 * 32 + r) * LDK + ks * 16 + 8 * h); s[t2] = MFMA32(a, qf[ks], s[t2]); }
;   }
;   float mx = m;
; #pragma unroll
;   for (int t2 = 0; t2 < 2; ++t2)
; #pragma unroll
;     for (int i = 0; i < 16; ++i) { const int kpos = k0 + t2 * 32 + crow(i, h); const bool ok = (kpos <= qpos) && (window == 0 || qpos - kpos < window);
;       const float v = ok ? s[t2][i] * sl2 : -1e30f; s[t2][i] = v; mx = fmaxf(mx, v); }
	s_nop 0
	v_mfma_f32_32x32x16_bf16 v[16:31], v[76:79], v[80:83], v[16:31]
	v_cvt_pk_bf16_f32 v79, v162, v161
	v_cvt_pk_bf16_f32 v78, v218, v216
	v_cvt_pk_bf16_f32 v77, v95, v94
	v_cvt_pk_bf16_f32 v76, v93, v92
	v_sub_f32_e32 v80, v91, v211
	v_exp_f32_e32 v80, v80
	v_mfma_f32_32x32x16_bf16 v[48:63], v[132:135], v[76:79], v[48:63]
	v_mov_b32_e32 v161, v87
	s_nop 1
	v_mov_b32_e32 v163, v80
	v_sub_f32_e32 v80, v88, v211
	s_waitcnt lgkmcnt(2)
	v_mfma_f32_32x32x16_bf16 v[16:31], v[72:75], v[76:79], v[16:31]
	v_cvt_pk_bf16_f32 v75, v86, v159
	v_cvt_pk_bf16_f32 v74, v85, v84
	v_cvt_pk_bf16_f32 v73, v223, v222
	v_cvt_pk_bf16_f32 v72, v221, v220
	s_waitcnt lgkmcnt(1)
	s_nop 0
	v_mfma_f32_32x32x16_bf16 v[48:63], v[68:71], v[72:75], v[48:63]
	v_exp_f32_e32 v68, v80
	v_sub_f32_e32 v69, v89, v211
	v_exp_f32_e32 v69, v69
	v_mov_b32_e32 v165, v68
	s_waitcnt lgkmcnt(0)
	v_mfma_f32_32x32x16_bf16 v[16:31], v[64:67], v[72:75], v[16:31]
	v_mov_b32_e32 v167, v69
	ds_read2_b64 v[64:67], v209 offset0:12 offset1:14
	v_cvt_pk_bf16_f32 v71, v167, v165
	v_cvt_pk_bf16_f32 v69, v153, v151
	v_cvt_pk_bf16_f32 v68, v157, v155
	ds_read2_b64 v[72:75], v210 offset0:44 offset1:46
	v_cvt_pk_bf16_f32 v70, v163, v161
	s_waitcnt lgkmcnt(1)
	s_nop 0
	v_mfma_f32_32x32x16_bf16 v[48:63], v[64:67], v[68:71], v[48:63]
	v_add_f32_e32 v64, v221, v219
	v_add_f32_e32 v64, v220, v64
	v_add_f32_e32 v64, v223, v64
	v_add_f32_e32 v64, v222, v64
	v_add_f32_e32 v64, v85, v64
	v_add_f32_e32 v64, v84, v64
	v_add_f32_e32 v169, v86, v64
	s_waitcnt lgkmcnt(0)
	v_mfma_f32_32x32x16_bf16 v[16:31], v[72:75], v[68:71], v[16:31]
	ds_read_b128 v[64:67], v206 offset:5120
	ds_read_b128 v[80:83], v206 offset:5152
	s_waitcnt lgkmcnt(1)
	v_mfma_f32_32x32x16_bf16 v[64:79], v[64:67], v[100:103], 0
	s_waitcnt vmcnt(0) lgkmcnt(0)
	v_mfma_f32_32x32x16_bf16 v[64:79], v[80:83], v[108:111], v[64:79]
	ds_read_b128 v[80:83], v206 offset:7680
	ds_read_b128 v[216:219], v206 offset:7712
	ds_read2_b64 v[136:139], v209 offset1:2
	ds_read2_b64 v[132:135], v209 offset0:4 offset1:6
	s_waitcnt lgkmcnt(3)
	v_mfma_f32_32x32x16_bf16 v[80:95], v[80:83], v[100:103], 0
	s_nop 5
	v_mul_f32_e32 v154, 0x3e8293ee, v64
	v_mul_f32_e32 v156, 0x3e8293ee, v65
	v_cndmask_b32_e64 v156, v189, v156, s[84:85]
	v_cndmask_b32_e64 v154, v154, v189, s[86:87]
	s_waitcnt lgkmcnt(2)
	v_mfma_f32_32x32x16_bf16 v[80:95], v[216:219], v[108:111], v[80:95]
	s_nop 11
	v_pk_mul_f32 v[64:65], v[88:89], s[2:3] op_sel_hi:[1,0]
	s_nop 0
	v_cndmask_b32_e64 v88, v65, v189, s[0:1]
	v_cndmask_b32_e64 v89, v64, v189, s[38:39]
	v_pk_mul_f32 v[64:65], v[90:91], s[2:3] op_sel_hi:[1,0]
	s_nop 0
	v_cndmask_b32_e64 v90, v65, v189, s[40:41]
	v_cndmask_b32_e64 v91, v64, v189, s[42:43]
	v_pk_mul_f32 v[64:65], v[92:93], s[2:3] op_sel_hi:[1,0]
	s_nop 0
	v_cndmask_b32_e64 v92, v65, v189, s[44:45]
	v_cndmask_b32_e64 v93, v64, v189, s[46:47]
	v_pk_mul_f32 v[64:65], v[94:95], s[2:3] op_sel_hi:[1,0]
	s_nop 0
	v_cndmask_b32_e64 v94, v65, v189, s[48:49]
	v_cndmask_b32_e64 v95, v64, v189, s[50:51]
	v_pk_mul_f32 v[64:65], v[80:81], s[2:3] op_sel_hi:[1,0]
	s_nop 0
	v_cndmask_b32_e64 v80, v65, v189, s[52:53]
	v_cndmask_b32_e64 v81, v64, v189, s[54:55]
	v_pk_mul_f32 v[64:65], v[82:83], s[2:3] op_sel_hi:[1,0]
	s_nop 0
	v_cndmask_b32_e64 v82, v65, v189, s[56:57]
	v_cndmask_b32_e64 v83, v64, v189, s[58:59]
	v_pk_mul_f32 v[64:65], v[84:85], s[2:3] op_sel_hi:[1,0]
	s_nop 0
	v_cndmask_b32_e64 v84, v65, v189, s[60:61]
	v_cndmask_b32_e64 v85, v64, v189, s[62:63]
	v_pk_mul_f32 v[64:65], v[86:87], s[2:3] op_sel_hi:[1,0]
	s_nop 0
	v_cndmask_b32_e64 v86, v65, v189, s[64:65]
	v_cndmask_b32_e64 v87, v64, v189, s[66:67]
	v_pk_mul_f32 v[64:65], v[72:73], s[2:3] op_sel_hi:[1,0]
	v_max3_f32 v72, v150, v154, v156
	v_cndmask_b32_e64 v158, v65, v189, s[68:69]
	v_cndmask_b32_e64 v160, v64, v189, s[70:71]
	v_pk_mul_f32 v[64:65], v[74:75], s[2:3] op_sel_hi:[1,0]
	s_nop 0
	v_cndmask_b32_e64 v162, v65, v189, s[72:73]
	v_cndmask_b32_e64 v164, v64, v189, s[74:75]
	v_pk_mul_f32 v[64:65], v[76:77], s[2:3] op_sel_hi:[1,0]
	s_nop 0
	v_cndmask_b32_e64 v166, v65, v189, s[76:77]
	v_cndmask_b32_e64 v168, v64, v189, s[78:79]
	v_pk_mul_f32 v[64:65], v[78:79], s[2:3] op_sel_hi:[1,0]
	s_nop 0
	v_cndmask_b32_e64 v216, v65, v189, s[80:81]
	v_cndmask_b32_e64 v217, v64, v189, s[82:83]
	v_pk_mul_f32 v[64:65], v[66:67], s[2:3] op_sel_hi:[1,0]
	s_nop 0
	v_cndmask_b32_e64 v218, v65, v189, s[88:89]
	v_cndmask_b32_e64 v219, v64, v189, s[90:91]
	v_pk_mul_f32 v[64:65], v[68:69], s[2:3] op_sel_hi:[1,0]
	v_max3_f32 v66, v72, v219, v218
	v_cndmask_b32_e64 v220, v65, v189, s[92:93]
	v_cndmask_b32_e64 v221, v64, v189, s[94:95]
	v_pk_mul_f32 v[64:65], v[70:71], s[2:3] op_sel_hi:[1,0]
	v_max3_f32 v66, v66, v221, v220
	v_cndmask_b32_e64 v222, v65, v189, s[96:97]
	v_cndmask_b32_e32 v223, v64, v189, vcc
	v_max3_f32 v64, v66, v223, v222
	v_max3_f32 v64, v64, v160, v158
	v_max3_f32 v64, v64, v164, v162
	v_max3_f32 v64, v64, v168, v166
	v_max3_f32 v64, v64, v217, v216
	v_max3_f32 v64, v64, v81, v80
	v_max3_f32 v64, v64, v83, v82
	v_max3_f32 v64, v64, v85, v84
	v_max3_f32 v64, v64, v87, v86
	v_max3_f32 v64, v64, v89, v88
	v_max3_f32 v64, v64, v91, v90
	v_max3_f32 v64, v64, v93, v92
	v_max3_f32 v224, v64, v95, v94
	ds_bpermute_b32 v152, v152, v224
	ds_read2_b64 v[76:79], v210 offset0:32 offset1:34
	ds_read2_b64 v[72:75], v210 offset0:36 offset1:38
	ds_read2_b64 v[68:71], v209 offset0:8 offset1:10
	ds_read2_b64 v[64:67], v210 offset0:40 offset1:42
	s_waitcnt lgkmcnt(4)
; DI float fexp2(float x) { return __builtin_amdgcn_exp2f(x); }
; #define MFMA32(a, b, c) __builtin_amdgcn_mfma_f32_32x32x16_bf16((a), (b), (c), 0, 0, 0)
; DI void pv_accum(const f32x16 (&s)[2], const bf16_t* sV, int r, int h, f32x16 (&O)[2]) {
;     ...
;       const bf16x8 pf = pack8(s[t2], s2);
; #pragma unroll
;       for (int dt = 0; dt < 2; ++dt) {
;         const bf16_t* vp = sV + (dt * 32 + r) * 68 + t2 * 32 + 16 * s2 + 4 * h;
;         const s16x4 lo = *(const s16x4*)vp, hi = *(const s16x4*)(vp + 8);
;         const bf16x8 vf = __builtin_shufflevector(lo, hi, 0, 1, 2, 3, 4, 5, 6, 7);
;         O[dt] = MFMA32(vf, pf, O[dt]);
; template <int DQK>
; DI void attn_tile_step(const bf16_t* sK, const bf16_t* sV, const bf16x8 (&qf)[DQK / 16], int k0, int qpos, int window, float sl2, float& m, float& lsum, f32x16 (&O)[2], int r, int h) {
;     ...
;       const float v = ok ? s[t2][i] * sl2 : -1e30f; s[t2][i] = v; mx = fmaxf(mx, v); }
;   mx = fmaxf(mx, __shfl_xor(mx, 32));
;   const float corr = fexp2(m - mx); m = mx; float ps = 0.f;
; #pragma unroll
;   for (int t2 = 0; t2 < 2; ++t2)
; #pragma unroll
;     for (int i = 0; i < 16; ++i) { const float pv = (s[t2][i] > -1e29f) ? fexp2(s[t2][i] - mx) : 0.f; s[t2][i] = pv; ps += pv; }
;   lsum = lsum * corr + ps;
; #pragma unroll
;   for (int dt = 0; dt < 2; ++dt)
; #pragma unroll
;     for (int i = 0; i < 16; ++i) O[dt][i] *= corr;
;   pv_accum(s, sV, r, h, O);
	v_max_f32_e32 v152, v152, v152
	v_max_f32_e32 v224, v224, v152
	v_sub_f32_e32 v225, v150, v224
	v_sub_f32_e32 v150, v156, v224
	v_exp_f32_e32 v150, v150
	v_sub_f32_e32 v152, v154, v224
	v_exp_f32_e32 v152, v152
	v_mov_b32_e32 v226, v150
	v_sub_f32_e32 v154, v219, v224
	v_exp_f32_e32 v154, v154
	v_mov_b32_e32 v227, v152
	v_sub_f32_e32 v152, v218, v224
	v_exp_f32_e32 v152, v152
	v_add_f32_e32 v150, 0, v227
	v_add_f32_e32 v150, v226, v150
	v_mov_b32_e32 v218, v152
	v_sub_f32_e32 v152, v220, v224
	v_exp_f32_e32 v152, v152
	s_nop 1
	v_mov_b32_e32 v219, v154
	v_sub_f32_e32 v154, v221, v224
	v_exp_f32_e32 v154, v154
	v_add_f32_e32 v150, v219, v150
	v_add_f32_e32 v150, v218, v150
	v_mov_b32_e32 v220, v152
	v_sub_f32_e32 v152, v222, v224
	v_exp_f32_e32 v152, v152
	s_nop 1
	v_mov_b32_e32 v221, v154
	v_sub_f32_e32 v154, v223, v224
	v_exp_f32_e32 v154, v154
	v_add_f32_e32 v150, v221, v150
	v_add_f32_e32 v150, v220, v150
	v_mov_b32_e32 v222, v152
	v_sub_f32_e32 v152, v158, v224
	v_exp_f32_e32 v152, v152
	s_nop 1
	v_mov_b32_e32 v223, v154
	v_sub_f32_e32 v154, v160, v224
	v_exp_f32_e32 v154, v154
	v_add_f32_e32 v150, v223, v150
	v_add_f32_e32 v150, v222, v150
	v_mov_b32_e32 v228, v152
	v_sub_f32_e32 v152, v162, v224
	v_exp_f32_e32 v152, v152
	s_nop 1
	v_mov_b32_e32 v160, v154
	v_sub_f32_e32 v154, v164, v224
	v_exp_f32_e32 v154, v154
	v_add_f32_e32 v150, v160, v150
	v_add_f32_e32 v150, v228, v150
	v_mov_b32_e32 v162, v152
	v_sub_f32_e32 v152, v166, v224
	v_exp_f32_e32 v152, v152
	s_nop 1
	v_mov_b32_e32 v164, v154
	v_sub_f32_e32 v154, v168, v224
	v_exp_f32_e32 v154, v154
	v_add_f32_e32 v150, v164, v150
	v_add_f32_e32 v150, v162, v150
	v_mov_b32_e32 v166, v152
	v_sub_f32_e32 v152, v216, v224
	v_exp_f32_e32 v152, v152
	s_nop 1
	v_mov_b32_e32 v229, v154
	v_sub_f32_e32 v154, v217, v224
	v_exp_f32_e32 v154, v154
	v_add_f32_e32 v150, v229, v150
	v_add_f32_e32 v150, v166, v150
	v_mov_b32_e32 v216, v152
	v_sub_f32_e32 v152, v80, v224
	v_exp_f32_e32 v152, v152
	s_nop 1
	v_mov_b32_e32 v217, v154
	v_sub_f32_e32 v154, v81, v224
	v_exp_f32_e32 v154, v154
	v_add_f32_e32 v150, v217, v150
	v_add_f32_e32 v150, v216, v150
	v_mov_b32_e32 v230, v152
	v_sub_f32_e32 v81, v82, v224
	v_exp_f32_e32 v81, v81
	v_mov_b32_e32 v231, v154
	v_add_f32_e32 v80, v231, v150
	v_sub_f32_e32 v150, v83, v224
	v_exp_f32_e32 v150, v150
	v_sub_f32_e32 v82, v85, v224
	v_mov_b32_e32 v232, v81
	v_sub_f32_e32 v81, v84, v224
	v_exp_f32_e32 v81, v81
	v_exp_f32_e32 v82, v82
	v_add_f32_e32 v80, v230, v80
	v_mov_b32_e32 v233, v150
	v_add_f32_e32 v80, v233, v80
	v_add_f32_e32 v80, v232, v80
	v_mov_b32_e32 v234, v81
	v_sub_f32_e32 v81, v86, v224
	v_exp_f32_e32 v81, v81
	v_mov_b32_e32 v235, v82
	v_sub_f32_e32 v82, v87, v224
	v_exp_f32_e32 v82, v82
	v_add_f32_e32 v80, v235, v80
	v_add_f32_e32 v80, v234, v80
	v_mov_b32_e32 v158, v81
	v_sub_f32_e32 v81, v89, v224
	v_exp_f32_e32 v81, v81
	v_mov_b32_e32 v86, v82
	v_add_f32_e32 v168, v86, v80
	v_sub_f32_e32 v80, v88, v224
	v_exp_f32_e32 v80, v80
	s_nop 0
	v_mov_b32_e32 v154, v80
	v_sub_f32_e32 v80, v90, v224
	v_exp_f32_e32 v80, v80
	v_mov_b32_e32 v156, v81
	v_sub_f32_e32 v81, v91, v224
	v_exp_f32_e32 v81, v81
	v_mov_b32_e32 v150, v80
	v_sub_f32_e32 v80, v93, v224
	v_exp_f32_e32 v87, v80
	v_exp_f32_e32 v80, v225
	v_mov_b32_e32 v152, v81
	v_sub_f32_e32 v81, v92, v224
	v_exp_f32_e32 v88, v81
	v_mov_b32_e32 v81, v142
	v_pk_mul_f32 v[46:47], v[46:47], v[80:81] op_sel_hi:[1,0]
	v_pk_mul_f32 v[44:45], v[44:45], v[80:81] op_sel_hi:[1,0]
	v_pk_mul_f32 v[42:43], v[42:43], v[80:81] op_sel_hi:[1,0]
	v_pk_mul_f32 v[40:41], v[40:41], v[80:81] op_sel_hi:[1,0]
	v_pk_mul_f32 v[38:39], v[38:39], v[80:81] op_sel_hi:[1,0]
	v_pk_mul_f32 v[36:37], v[36:37], v[80:81] op_sel_hi:[1,0]
	v_pk_mul_f32 v[34:35], v[34:35], v[80:81] op_sel_hi:[1,0]
	v_pk_mul_f32 v[32:33], v[32:33], v[80:81] op_sel_hi:[1,0]
	v_cvt_pk_bf16_f32 v85, v223, v222
	v_cvt_pk_bf16_f32 v84, v221, v220
	v_cvt_pk_bf16_f32 v83, v219, v218
	v_cvt_pk_bf16_f32 v82, v227, v226
	v_pk_mul_f32 v[14:15], v[14:15], v[80:81] op_sel_hi:[1,0]
	v_pk_mul_f32 v[12:13], v[12:13], v[80:81] op_sel_hi:[1,0]
	v_mfma_f32_32x32x16_bf16 v[32:47], v[136:139], v[82:85], v[32:47]
	v_mul_f32_e64 v10, v10, v80
	v_mul_f32_e64 v11, v11, v80
	v_mul_f32_e64 v8, v8, v80
	v_mul_f32_e64 v9, v9, v80
	v_mul_f32_e64 v6, v6, v80
	v_mul_f32_e64 v7, v7, v80
	v_pk_mul_f32 v[4:5], v[4:5], v[80:81] op_sel_hi:[1,0]
	v_pk_mul_f32 v[2:3], v[2:3], v[80:81] op_sel_hi:[1,0]
	v_pk_mul_f32 v[0:1], v[0:1], v[80:81] op_sel_hi:[1,0]
	s_waitcnt lgkmcnt(3)
	s_nop 0
	v_mfma_f32_32x32x16_bf16 v[0:15], v[76:79], v[82:85], v[0:15]
	v_cvt_pk_bf16_f32 v79, v217, v216
	v_cvt_pk_bf16_f32 v78, v229, v166
	v_cvt_pk_bf16_f32 v77, v164, v162
	v_cvt_pk_bf16_f32 v76, v160, v228
	v_sub_f32_e32 v83, v94, v224
	v_sub_f32_e32 v82, v95, v224
	v_mfma_f32_32x32x16_bf16 v[32:47], v[132:135], v[76:79], v[32:47]
	v_exp_f32_e32 v83, v83
	v_exp_f32_e32 v82, v82
	v_mov_b32_e32 v160, v88
	s_nop 1
	v_mov_b32_e32 v162, v87
	s_waitcnt lgkmcnt(2)
	v_mfma_f32_32x32x16_bf16 v[0:15], v[72:75], v[76:79], v[0:15]
	v_cvt_pk_bf16_f32 v75, v86, v158
	v_cvt_pk_bf16_f32 v74, v235, v234
	v_cvt_pk_bf16_f32 v73, v233, v232
	v_cvt_pk_bf16_f32 v72, v231, v230
	s_waitcnt lgkmcnt(1)
	s_nop 0
	v_mfma_f32_32x32x16_bf16 v[32:47], v[68:71], v[72:75], v[32:47]
	v_mov_b32_e32 v164, v83
	v_add_f32_e64 v68, v158, v168
	v_add_f32_e64 v69, v159, v169
	v_mov_b32_e32 v166, v82
	v_pk_add_f32 v[68:69], v[156:157], v[68:69]
	v_pk_add_f32 v[76:77], v[154:155], v[68:69]
	s_waitcnt lgkmcnt(0)
	v_mfma_f32_32x32x16_bf16 v[0:15], v[64:67], v[72:75], v[0:15]
	ds_read2_b64 v[64:67], v209 offset0:12 offset1:14
	v_cvt_pk_bf16_f32 v71, v166, v164
	v_cvt_pk_bf16_f32 v69, v152, v150
	v_cvt_pk_bf16_f32 v68, v156, v154
	ds_read2_b64 v[72:75], v210 offset0:44 offset1:46
	v_cvt_pk_bf16_f32 v70, v162, v160
	s_waitcnt lgkmcnt(1)
	s_nop 0
	v_mfma_f32_32x32x16_bf16 v[32:47], v[64:67], v[68:71], v[32:47]
	v_add_f32_e64 v64, v152, v76
	v_add_f32_e64 v65, v153, v77
	v_add_f32_e64 v64, v150, v64
	v_add_f32_e64 v65, v151, v65
	v_add_f32_e64 v64, v162, v64
	v_add_f32_e64 v65, v163, v65
	v_pk_add_f32 v[64:65], v[160:161], v[64:65]
	s_waitcnt lgkmcnt(0)
	v_mfma_f32_32x32x16_bf16 v[0:15], v[72:75], v[68:71], v[0:15]
	v_add_f32_e64 v64, v166, v64
	v_add_f32_e64 v65, v167, v65
	v_add_f32_e64 v64, v164, v64
	v_add_f32_e64 v65, v165, v65
	v_fma_f32 v146, v146, v80, v64
	v_fma_f32 v147, v147, v81, v65
	v_mov_b32_e32 v151, v211
	v_mov_b32_e32 v150, v224
	s_branch .LBB0_536
